# speedup vs baseline: 1.0048x; 1.0048x over previous
.LBB0_197:
	s_mov_b32 s79, s10
	s_lshl_b32 s3, s86, 13
	s_mul_i32 s10, s86, 0xffffe100
	s_add_i32 s10, s3, s10
	v_or_b32_e32 v36, s3, v156
	v_lshl_or_b32 v44, v157, 2, s10
	v_or_b32_e32 v238, s3, v155
	v_or_b32_e32 v239, s3, v154
	v_or_b32_e32 v240, s3, v153
	ds_read_b128 v[206:209], v36 offset:24576
	ds_read_b128 v[48:51], v44 offset:51200
	ds_read_b128 v[52:55], v44 offset:51232
	ds_read_b128 v[56:59], v44 offset:51264
	ds_read_b128 v[60:63], v44 offset:51296
	ds_read_b128 v[210:213], v36 offset:28672
	ds_read_b128 v[32:35], v44 offset:51328
	ds_read_b128 v[36:39], v44 offset:51360
	ds_read_b128 v[40:43], v44 offset:51392
	ds_read_b128 v[44:47], v44 offset:51424
	ds_read_b128 v[214:217], v238 offset:24576
	ds_read_b128 v[218:221], v238 offset:28672
	ds_read_b128 v[222:225], v239 offset:24576
	ds_read_b128 v[226:229], v239 offset:28672
	ds_read_b128 v[230:233], v240 offset:24576
	s_add_i32 s81, s18, s19
	s_add_i32 s10, s81, 2
	v_add_u32_e32 v192, s78, v128
	v_add_f32_e32 v64, 0, v188
	v_add_f32_e32 v64, v190, v64
	v_add_f32_e32 v64, v186, v64
	v_add_f32_e32 v64, v189, v64
	v_add_f32_e32 v64, v184, v64
	v_add_f32_e32 v64, v187, v64
	v_add_f32_e32 v64, v183, v64
	v_add_f32_e32 v64, v185, v64
	v_add_f32_e32 v64, v171, v64
	s_waitcnt lgkmcnt(10)
	v_mfma_f32_32x32x16_bf16 v[48:63], v[206:209], v[96:99], v[48:63]
	v_add_f32_e32 v64, v180, v64
	v_add_f32_e32 v64, v170, v64
	v_add_f32_e32 v64, v172, v64
	v_exp_f32_e32 v72, v140
	v_add_f32_e32 v64, v169, v64
	v_exp_f32_e32 v73, v141
	v_add_f32_e32 v64, v182, v64
	v_exp_f32_e32 v74, v138
	v_add_f32_e32 v64, v173, v64
	ds_read_b128 v[234:237], v240 offset:28672
	s_waitcnt lgkmcnt(6)
	v_mfma_f32_32x32x16_bf16 v[32:47], v[210:213], v[96:99], v[32:47]
	v_exp_f32_e32 v75, v139
	v_add_f32_e32 v64, v181, v64
	v_exp_f32_e32 v76, v136
	v_add_f32_e32 v64, v72, v64
	v_exp_f32_e32 v77, v137
	v_add_f32_e32 v64, v73, v64
	v_exp_f32_e32 v78, v134
	v_add_f32_e32 v64, v74, v64
	v_exp_f32_e32 v79, v135
	s_waitcnt lgkmcnt(5)
	v_mfma_f32_32x32x16_bf16 v[48:63], v[214:217], v[100:103], v[48:63]
	v_add_f32_e32 v64, v75, v64
	v_exp_f32_e32 v80, v94
	v_add_f32_e32 v64, v76, v64
	v_exp_f32_e32 v81, v95
	v_add_f32_e32 v64, v77, v64
	v_exp_f32_e32 v82, v90
	v_add_f32_e32 v64, v78, v64
	v_exp_f32_e32 v83, v91
	v_add_f32_e32 v64, v79, v64
	s_waitcnt lgkmcnt(4)
	v_mfma_f32_32x32x16_bf16 v[32:47], v[218:221], v[100:103], v[32:47]
	v_exp_f32_e32 v84, v88
	v_add_f32_e32 v64, v80, v64
	v_exp_f32_e32 v85, v89
	v_add_f32_e32 v64, v81, v64
	v_exp_f32_e32 v86, v86
	v_add_f32_e32 v64, v82, v64
	v_exp_f32_e32 v87, v87
	v_add_f32_e32 v64, v83, v64
	v_add_f32_e32 v64, v84, v64
	s_waitcnt lgkmcnt(3)
	v_mfma_f32_32x32x16_bf16 v[48:63], v[222:225], v[104:107], v[48:63]
	v_add_f32_e32 v64, v85, v64
	v_add_f32_e32 v64, v86, v64
	v_add_f32_e32 v167, v87, v64
	v_mov_b32_e32 v168, v167
	v_cvt_pk_bf16_f32 v64, v188, v190
	v_cvt_pk_bf16_f32 v65, v186, v189
	v_cvt_pk_bf16_f32 v66, v184, v187
	v_cvt_pk_bf16_f32 v67, v183, v185
	v_cvt_pk_bf16_f32 v68, v171, v180
	s_waitcnt lgkmcnt(2)
	v_mfma_f32_32x32x16_bf16 v[32:47], v[226:229], v[104:107], v[32:47]
	v_cvt_pk_bf16_f32 v69, v170, v172
	v_cvt_pk_bf16_f32 v70, v169, v182
	v_cvt_pk_bf16_f32 v71, v173, v181
	v_cvt_pk_bf16_f32 v72, v72, v73
	v_cvt_pk_bf16_f32 v73, v74, v75
	v_cvt_pk_bf16_f32 v74, v76, v77
	v_cvt_pk_bf16_f32 v75, v78, v79
	v_cvt_pk_bf16_f32 v76, v80, v81
	v_cvt_pk_bf16_f32 v77, v82, v83
	s_waitcnt lgkmcnt(1)
	v_mfma_f32_32x32x16_bf16 v[48:63], v[230:233], v[108:111], v[48:63]
	v_cvt_pk_bf16_f32 v78, v84, v85
	v_cvt_pk_bf16_f32 v79, v86, v87
	s_nop 1
	v_permlane32_swap_b32_e32 v167, v168
	v_permlane32_swap_b32_e32 v64, v66
	v_permlane32_swap_b32_e32 v65, v67
	v_permlane32_swap_b32_e32 v68, v70
	v_permlane32_swap_b32_e32 v69, v71
	v_permlane32_swap_b32_e32 v72, v74
	v_permlane32_swap_b32_e32 v73, v75
	s_waitcnt lgkmcnt(0)
	v_mfma_f32_32x32x16_bf16 v[32:47], v[234:237], v[108:111], v[32:47]
	v_permlane32_swap_b32_e32 v76, v78
	v_permlane32_swap_b32_e32 v77, v79
	s_cmp_lt_i32 s10, 0
	s_cbranch_scc1 .LBB0_199
	v_add_u32_e32 v242, 0x60, v192
	v_add_u32_e32 v241, 64, v192
	v_cmp_le_i32_e32 vcc, v242, v152
	s_nop 7
	v_cndmask_b32_e32 v32, v176, v32, vcc
	v_cmp_lt_i32_e32 vcc, v241, v152
	s_nop 1
	v_cndmask_b32_e32 v49, v176, v49, vcc
	v_cmp_le_i32_e32 vcc, v241, v152
	v_add_u32_e32 v241, 0x61, v192
	s_nop 0
	v_cndmask_b32_e32 v48, v176, v48, vcc
	v_cmp_le_i32_e32 vcc, v241, v152
	v_add_u32_e32 v241, 0x42, v192
	s_nop 0
	v_cndmask_b32_e32 v33, v176, v33, vcc
	v_cmp_le_i32_e32 vcc, v241, v152
	v_add_u32_e32 v241, 0x62, v192
	s_nop 0
	v_cndmask_b32_e32 v50, v176, v50, vcc
	v_cmp_le_i32_e32 vcc, v241, v152
	v_add_u32_e32 v241, 0x43, v192
	s_nop 0
	v_cndmask_b32_e32 v34, v176, v34, vcc
	v_cmp_le_i32_e32 vcc, v241, v152
	v_add_u32_e32 v241, 0x63, v192
	s_nop 0
	v_cndmask_b32_e32 v51, v176, v51, vcc
	v_cmp_le_i32_e32 vcc, v241, v152
	v_add_u32_e32 v241, 0x48, v192
	s_nop 0
	v_cndmask_b32_e32 v35, v176, v35, vcc
	v_cmp_le_i32_e32 vcc, v241, v152
	v_add_u32_e32 v241, 0x68, v192
	s_nop 0
	v_cndmask_b32_e32 v52, v176, v52, vcc
	v_cmp_le_i32_e32 vcc, v241, v152
	v_add_u32_e32 v241, 0x49, v192
	s_nop 0
	v_cndmask_b32_e32 v36, v176, v36, vcc
	v_cmp_le_i32_e32 vcc, v241, v152
	v_add_u32_e32 v241, 0x69, v192
	s_nop 0
	v_cndmask_b32_e32 v53, v176, v53, vcc
	v_cmp_le_i32_e32 vcc, v241, v152
	v_add_u32_e32 v241, 0x4a, v192
	s_nop 0
	v_cndmask_b32_e32 v37, v176, v37, vcc
	v_cmp_le_i32_e32 vcc, v241, v152
	v_add_u32_e32 v241, 0x6a, v192
	s_nop 0
	v_cndmask_b32_e32 v54, v176, v54, vcc
	v_cmp_le_i32_e32 vcc, v241, v152
	v_add_u32_e32 v241, 0x4b, v192
	s_nop 0
	v_cndmask_b32_e32 v38, v176, v38, vcc
	v_cmp_le_i32_e32 vcc, v241, v152
	v_add_u32_e32 v241, 0x6b, v192
	s_nop 0
	v_cndmask_b32_e32 v55, v176, v55, vcc
	v_cmp_le_i32_e32 vcc, v241, v152
	v_add_u32_e32 v241, 0x50, v192
	s_nop 0
	v_cndmask_b32_e32 v39, v176, v39, vcc
	v_cmp_le_i32_e32 vcc, v241, v152
	v_add_u32_e32 v241, 0x70, v192
	s_nop 0
	v_cndmask_b32_e32 v56, v176, v56, vcc
	v_cmp_le_i32_e32 vcc, v241, v152
	v_add_u32_e32 v241, 0x51, v192
	s_nop 0
	v_cndmask_b32_e32 v40, v176, v40, vcc
	v_cmp_le_i32_e32 vcc, v241, v152
	v_add_u32_e32 v241, 0x71, v192
	s_nop 0
	v_cndmask_b32_e32 v57, v176, v57, vcc
	v_cmp_le_i32_e32 vcc, v241, v152
	v_add_u32_e32 v241, 0x52, v192
	s_nop 0
	v_cndmask_b32_e32 v41, v176, v41, vcc
	v_cmp_le_i32_e32 vcc, v241, v152
	v_add_u32_e32 v241, 0x72, v192
	s_nop 0
	v_cndmask_b32_e32 v58, v176, v58, vcc
	v_cmp_le_i32_e32 vcc, v241, v152
	v_add_u32_e32 v241, 0x53, v192
	s_nop 0
	v_cndmask_b32_e32 v42, v176, v42, vcc
	v_cmp_le_i32_e32 vcc, v241, v152
	v_add_u32_e32 v241, 0x73, v192
	s_nop 0
	v_cndmask_b32_e32 v59, v176, v59, vcc
	v_cmp_le_i32_e32 vcc, v241, v152
	v_add_u32_e32 v241, 0x58, v192
	s_nop 0
	v_cndmask_b32_e32 v43, v176, v43, vcc
	v_cmp_le_i32_e32 vcc, v241, v152
	v_add_u32_e32 v241, 0x78, v192
	s_nop 0
	v_cndmask_b32_e32 v60, v176, v60, vcc
	v_cmp_le_i32_e32 vcc, v241, v152
	v_add_u32_e32 v241, 0x59, v192
	s_nop 0
	v_cndmask_b32_e32 v44, v176, v44, vcc
	v_cmp_le_i32_e32 vcc, v241, v152
	v_add_u32_e32 v241, 0x79, v192
	s_nop 0
	v_cndmask_b32_e32 v61, v176, v61, vcc
	v_cmp_le_i32_e32 vcc, v241, v152
	v_add_u32_e32 v241, 0x5a, v192
	s_nop 0
	v_cndmask_b32_e32 v45, v176, v45, vcc
	v_cmp_le_i32_e32 vcc, v241, v152
	v_add_u32_e32 v241, 0x7a, v192
	s_nop 0
	v_cndmask_b32_e32 v62, v176, v62, vcc
	v_cmp_le_i32_e32 vcc, v241, v152
	v_add_u32_e32 v241, 0x5b, v192
	s_nop 0
	v_cndmask_b32_e32 v46, v176, v46, vcc
	v_cmp_le_i32_e32 vcc, v241, v152
	v_add_u32_e32 v241, 0x7b, v192
	s_nop 0
	v_cndmask_b32_e32 v63, v176, v63, vcc
	v_cmp_le_i32_e32 vcc, v241, v152
	s_nop 1
	v_cndmask_b32_e32 v47, v176, v47, vcc
.LBB0_199:
	s_cmp_lt_i32 s19, s77
	s_cselect_b64 s[22:23], -1, 0
	s_cmp_ge_i32 s19, s77
	v_add_u32_e32 v135, s78, v158
	v_add_u32_e32 v134, s78, v166
	s_cbranch_scc1 .LBB0_201
	v_add_u32_e32 v80, 0xc0, v135
	v_ashrrev_i32_e32 v81, 31, v80
	v_lshlrev_b64 v[80:81], 11, v[80:81]
	v_lshl_or_b32 v80, v159, 1, v80
	v_lshl_add_u64 v[82:83], s[42:43], 0, v[80:81]
	v_lshl_add_u64 v[80:81], s[40:41], 0, v[80:81]
	global_load_dwordx4 v[112:115], v[82:83], off
	global_load_dwordx4 v[116:119], v[80:81], off
	v_add_u32_e32 v80, 0xc0, v134
	v_ashrrev_i32_e32 v81, 31, v80
	v_lshl_add_u64 v[80:81], v[80:81], 2, s[38:39]
	global_load_dword v160, v[80:81], off

.LBB0_207:
	s_waitcnt lgkmcnt(0)
	s_barrier
	s_mul_i32 s36, s79, 0xffffe100
	s_add_i32 s36, s87, s36
	v_add_u32_e32 v68, s87, v156
	v_lshl_add_u32 v76, v157, 2, s36
	v_add_u32_e32 v238, s87, v155
	v_add_u32_e32 v239, s87, v154
	v_add_u32_e32 v240, s87, v153
	ds_read_b128 v[206:209], v68 offset:24576
	ds_read_b128 v[80:83], v76 offset:51200
	ds_read_b128 v[84:87], v76 offset:51232
	ds_read_b128 v[88:91], v76 offset:51264
	ds_read_b128 v[92:95], v76 offset:51296
	ds_read_b128 v[210:213], v68 offset:28672
	ds_read_b128 v[64:67], v76 offset:51328
	ds_read_b128 v[68:71], v76 offset:51360
	ds_read_b128 v[72:75], v76 offset:51392
	ds_read_b128 v[76:79], v76 offset:51424
	ds_read_b128 v[214:217], v238 offset:24576
	ds_read_b128 v[218:221], v238 offset:28672
	ds_read_b128 v[222:225], v239 offset:24576
	ds_read_b128 v[226:229], v239 offset:28672
	ds_read_b128 v[230:233], v240 offset:24576
	s_add_i32 s81, s81, 3
	v_cndmask_b32_e64 v136, v136, v163, s[10:11]
	v_mul_f32_e32 v137, 0xbe38aa3b, v136
	v_fmamk_f32 v48, v48, 0x3e38aa3b, v137
	v_fmamk_f32 v49, v49, 0x3e38aa3b, v137
	v_fmamk_f32 v50, v50, 0x3e38aa3b, v137
	v_fmamk_f32 v51, v51, 0x3e38aa3b, v137
	v_fmamk_f32 v52, v52, 0x3e38aa3b, v137
	v_fmamk_f32 v53, v53, 0x3e38aa3b, v137
	v_fmamk_f32 v54, v54, 0x3e38aa3b, v137
	v_fmamk_f32 v55, v55, 0x3e38aa3b, v137
	v_fmamk_f32 v56, v56, 0x3e38aa3b, v137
	v_fmamk_f32 v57, v57, 0x3e38aa3b, v137
	v_fmamk_f32 v58, v58, 0x3e38aa3b, v137
	v_fmamk_f32 v59, v59, 0x3e38aa3b, v137
	s_waitcnt lgkmcnt(10)
	v_mfma_f32_32x32x16_bf16 v[80:95], v[206:209], v[96:99], v[80:95]
	v_fmamk_f32 v60, v60, 0x3e38aa3b, v137
	v_fmamk_f32 v61, v61, 0x3e38aa3b, v137
	v_fmamk_f32 v62, v62, 0x3e38aa3b, v137
	v_fmamk_f32 v63, v63, 0x3e38aa3b, v137
	v_fmamk_f32 v32, v32, 0x3e38aa3b, v137
	v_fmamk_f32 v33, v33, 0x3e38aa3b, v137
	v_fmamk_f32 v34, v34, 0x3e38aa3b, v137
	v_fmamk_f32 v35, v35, 0x3e38aa3b, v137
	v_fmamk_f32 v36, v36, 0x3e38aa3b, v137
	v_fmamk_f32 v37, v37, 0x3e38aa3b, v137
	v_fmamk_f32 v38, v38, 0x3e38aa3b, v137
	v_fmamk_f32 v39, v39, 0x3e38aa3b, v137
	v_fmamk_f32 v40, v40, 0x3e38aa3b, v137
	v_fmamk_f32 v41, v41, 0x3e38aa3b, v137
	ds_read_b128 v[234:237], v240 offset:28672
	s_waitcnt lgkmcnt(6)
	v_mfma_f32_32x32x16_bf16 v[64:79], v[210:213], v[96:99], v[64:79]
	v_fmamk_f32 v42, v42, 0x3e38aa3b, v137
	v_fmamk_f32 v43, v43, 0x3e38aa3b, v137
	v_fmamk_f32 v44, v44, 0x3e38aa3b, v137
	v_fmamk_f32 v45, v45, 0x3e38aa3b, v137
	v_fmamk_f32 v46, v46, 0x3e38aa3b, v137
	v_fmac_f32_e32 v137, 0x3e38aa3b, v47
	v_exp_f32_e32 v47, v48
	v_exp_f32_e32 v138, v49
	v_exp_f32_e32 v50, v50
	v_exp_f32_e32 v51, v51
	v_exp_f32_e32 v52, v52
	v_exp_f32_e32 v139, v32
	v_add_f32_e32 v32, 0, v47
	v_exp_f32_e32 v53, v53
	s_waitcnt lgkmcnt(5)
	v_mfma_f32_32x32x16_bf16 v[80:95], v[214:217], v[100:103], v[80:95]
	v_add_f32_e32 v32, v138, v32
	v_exp_f32_e32 v54, v54
	v_add_f32_e32 v32, v50, v32
	v_exp_f32_e32 v55, v55
	v_add_f32_e32 v32, v51, v32
	v_exp_f32_e32 v56, v56
	v_add_f32_e32 v32, v52, v32
	v_exp_f32_e32 v57, v57
	v_add_f32_e32 v32, v53, v32
	v_exp_f32_e32 v58, v58
	v_add_f32_e32 v32, v54, v32
	v_exp_f32_e32 v59, v59
	v_add_f32_e32 v32, v55, v32
	v_exp_f32_e32 v60, v60
	s_waitcnt lgkmcnt(4)
	v_mfma_f32_32x32x16_bf16 v[64:79], v[218:221], v[100:103], v[64:79]
	v_add_f32_e32 v32, v56, v32
	v_exp_f32_e32 v61, v61
	v_add_f32_e32 v32, v57, v32
	v_exp_f32_e32 v62, v62
	v_add_f32_e32 v32, v58, v32
	v_exp_f32_e32 v63, v63
	v_add_f32_e32 v32, v59, v32
	v_add_f32_e32 v32, v60, v32
	v_exp_f32_e32 v140, v33
	v_add_f32_e32 v32, v61, v32
	v_exp_f32_e32 v141, v34
	v_add_f32_e32 v32, v62, v32
	v_exp_f32_e32 v163, v35
	v_add_f32_e32 v32, v63, v32
	s_waitcnt lgkmcnt(3)
	v_mfma_f32_32x32x16_bf16 v[80:95], v[222:225], v[104:107], v[80:95]
	v_exp_f32_e32 v169, v36
	v_add_f32_e32 v32, v139, v32
	v_exp_f32_e32 v170, v37
	v_add_f32_e32 v32, v140, v32
	v_exp_f32_e32 v171, v38
	v_add_f32_e32 v32, v141, v32
	v_exp_f32_e32 v172, v39
	v_add_f32_e32 v32, v163, v32
	v_exp_f32_e32 v173, v40
	v_add_f32_e32 v32, v169, v32
	v_exp_f32_e32 v178, v41
	v_add_f32_e32 v32, v170, v32
	v_exp_f32_e32 v179, v42
	v_add_f32_e32 v32, v171, v32
	s_waitcnt lgkmcnt(2)
	v_mfma_f32_32x32x16_bf16 v[64:79], v[226:229], v[104:107], v[64:79]
	v_exp_f32_e32 v180, v43
	v_add_f32_e32 v32, v172, v32
	v_exp_f32_e32 v181, v44
	v_add_f32_e32 v32, v173, v32
	v_exp_f32_e32 v182, v45
	v_add_f32_e32 v32, v178, v32
	v_exp_f32_e32 v183, v46
	v_add_f32_e32 v32, v179, v32
	v_exp_f32_e32 v137, v137
	v_add_f32_e32 v32, v180, v32
	v_add_f32_e32 v32, v181, v32
	v_add_f32_e32 v32, v182, v32
	v_add_f32_e32 v32, v183, v32
	v_add_f32_e32 v48, v137, v32
	s_waitcnt lgkmcnt(1)
	v_mfma_f32_32x32x16_bf16 v[80:95], v[230:233], v[108:111], v[80:95]
	v_mov_b32_e32 v49, v48
	v_cvt_pk_bf16_f32 v32, v47, v138
	v_cvt_pk_bf16_f32 v33, v50, v51
	v_cvt_pk_bf16_f32 v34, v52, v53
	v_cvt_pk_bf16_f32 v35, v54, v55
	v_cvt_pk_bf16_f32 v36, v56, v57
	v_cvt_pk_bf16_f32 v37, v58, v59
	v_cvt_pk_bf16_f32 v38, v60, v61
	v_cvt_pk_bf16_f32 v39, v62, v63
	v_cvt_pk_bf16_f32 v40, v139, v140
	v_cvt_pk_bf16_f32 v41, v141, v163
	v_cvt_pk_bf16_f32 v42, v169, v170
	v_cvt_pk_bf16_f32 v43, v171, v172
	v_cvt_pk_bf16_f32 v44, v173, v178
	s_waitcnt lgkmcnt(0)
	v_mfma_f32_32x32x16_bf16 v[64:79], v[234:237], v[108:111], v[64:79]
	v_cvt_pk_bf16_f32 v45, v179, v180
	v_cvt_pk_bf16_f32 v46, v181, v182
	v_cvt_pk_bf16_f32 v47, v183, v137
	s_nop 1
	v_permlane32_swap_b32_e32 v48, v49
	v_permlane32_swap_b32_e32 v32, v34
	v_permlane32_swap_b32_e32 v33, v35
	v_permlane32_swap_b32_e32 v36, v38
	v_permlane32_swap_b32_e32 v37, v39
	v_permlane32_swap_b32_e32 v40, v42
	v_permlane32_swap_b32_e32 v41, v43
	v_permlane32_swap_b32_e32 v44, v46
	v_permlane32_swap_b32_e32 v45, v47
	s_cmp_lt_i32 s81, 0
	s_cbranch_scc1 .LBB0_209
	v_add_u32_e32 v242, 0xa0, v192
	v_add_u32_e32 v241, 0x80, v192
	v_cmp_le_i32_e32 vcc, v242, v152
	s_nop 7
	v_cndmask_b32_e32 v64, v176, v64, vcc
	v_cmp_lt_i32_e32 vcc, v241, v152
	s_nop 1
	v_cndmask_b32_e32 v81, v176, v81, vcc
	v_cmp_le_i32_e32 vcc, v241, v152
	v_add_u32_e32 v241, 0xa1, v192
	s_nop 0
	v_cndmask_b32_e32 v80, v176, v80, vcc
	v_cmp_le_i32_e32 vcc, v241, v152
	v_add_u32_e32 v241, 0x82, v192
	s_nop 0
	v_cndmask_b32_e32 v65, v176, v65, vcc
	v_cmp_le_i32_e32 vcc, v241, v152
	v_add_u32_e32 v241, 0xa2, v192
	s_nop 0
	v_cndmask_b32_e32 v82, v176, v82, vcc
	v_cmp_le_i32_e32 vcc, v241, v152
	v_add_u32_e32 v241, 0x83, v192
	s_nop 0
	v_cndmask_b32_e32 v66, v176, v66, vcc
	v_cmp_le_i32_e32 vcc, v241, v152
	v_add_u32_e32 v241, 0xa3, v192
	s_nop 0
	v_cndmask_b32_e32 v83, v176, v83, vcc
	v_cmp_le_i32_e32 vcc, v241, v152
	v_add_u32_e32 v241, 0x88, v192
	s_nop 0
	v_cndmask_b32_e32 v67, v176, v67, vcc
	v_cmp_le_i32_e32 vcc, v241, v152
	v_add_u32_e32 v241, 0xa8, v192
	s_nop 0
	v_cndmask_b32_e32 v84, v176, v84, vcc
	v_cmp_le_i32_e32 vcc, v241, v152
	v_add_u32_e32 v241, 0x89, v192
	s_nop 0
	v_cndmask_b32_e32 v68, v176, v68, vcc
	v_cmp_le_i32_e32 vcc, v241, v152
	v_add_u32_e32 v241, 0xa9, v192
	s_nop 0
	v_cndmask_b32_e32 v85, v176, v85, vcc
	v_cmp_le_i32_e32 vcc, v241, v152
	v_add_u32_e32 v241, 0x8a, v192
	s_nop 0
	v_cndmask_b32_e32 v69, v176, v69, vcc
	v_cmp_le_i32_e32 vcc, v241, v152
	v_add_u32_e32 v241, 0xaa, v192
	s_nop 0
	v_cndmask_b32_e32 v86, v176, v86, vcc
	v_cmp_le_i32_e32 vcc, v241, v152
	v_add_u32_e32 v241, 0x8b, v192
	s_nop 0
	v_cndmask_b32_e32 v70, v176, v70, vcc
	v_cmp_le_i32_e32 vcc, v241, v152
	v_add_u32_e32 v241, 0xab, v192
	s_nop 0
	v_cndmask_b32_e32 v87, v176, v87, vcc
	v_cmp_le_i32_e32 vcc, v241, v152
	v_add_u32_e32 v241, 0x90, v192
	s_nop 0
	v_cndmask_b32_e32 v71, v176, v71, vcc
	v_cmp_le_i32_e32 vcc, v241, v152
	v_add_u32_e32 v241, 0xb0, v192
	s_nop 0
	v_cndmask_b32_e32 v88, v176, v88, vcc
	v_cmp_le_i32_e32 vcc, v241, v152
	v_add_u32_e32 v241, 0x91, v192
	s_nop 0
	v_cndmask_b32_e32 v72, v176, v72, vcc
	v_cmp_le_i32_e32 vcc, v241, v152
	v_add_u32_e32 v241, 0xb1, v192
	s_nop 0
	v_cndmask_b32_e32 v89, v176, v89, vcc
	v_cmp_le_i32_e32 vcc, v241, v152
	v_add_u32_e32 v241, 0x92, v192
	s_nop 0
	v_cndmask_b32_e32 v73, v176, v73, vcc
	v_cmp_le_i32_e32 vcc, v241, v152
	v_add_u32_e32 v241, 0xb2, v192
	s_nop 0
	v_cndmask_b32_e32 v90, v176, v90, vcc
	v_cmp_le_i32_e32 vcc, v241, v152
	v_add_u32_e32 v241, 0x93, v192
	s_nop 0
	v_cndmask_b32_e32 v74, v176, v74, vcc
	v_cmp_le_i32_e32 vcc, v241, v152
	v_add_u32_e32 v241, 0xb3, v192
	s_nop 0
	v_cndmask_b32_e32 v91, v176, v91, vcc
	v_cmp_le_i32_e32 vcc, v241, v152
	v_add_u32_e32 v241, 0x98, v192
	s_nop 0
	v_cndmask_b32_e32 v75, v176, v75, vcc
	v_cmp_le_i32_e32 vcc, v241, v152
	v_add_u32_e32 v241, 0xb8, v192
	s_nop 0
	v_cndmask_b32_e32 v92, v176, v92, vcc
	v_cmp_le_i32_e32 vcc, v241, v152
	v_add_u32_e32 v241, 0x99, v192
	s_nop 0
	v_cndmask_b32_e32 v76, v176, v76, vcc
	v_cmp_le_i32_e32 vcc, v241, v152
	v_add_u32_e32 v241, 0xb9, v192
	s_nop 0
	v_cndmask_b32_e32 v93, v176, v93, vcc
	v_cmp_le_i32_e32 vcc, v241, v152
	v_add_u32_e32 v241, 0x9a, v192
	s_nop 0
	v_cndmask_b32_e32 v77, v176, v77, vcc
	v_cmp_le_i32_e32 vcc, v241, v152
	v_add_u32_e32 v241, 0xba, v192
	s_nop 0
	v_cndmask_b32_e32 v94, v176, v94, vcc
	v_cmp_le_i32_e32 vcc, v241, v152
	v_add_u32_e32 v241, 0x9b, v192
	s_nop 0
	v_cndmask_b32_e32 v78, v176, v78, vcc
	v_cmp_le_i32_e32 vcc, v241, v152
	v_add_u32_e32 v241, 0xbb, v192
	s_nop 0
	v_cndmask_b32_e32 v95, v176, v95, vcc
	v_cmp_le_i32_e32 vcc, v241, v152
	s_nop 1
	v_cndmask_b32_e32 v79, v176, v79, vcc
.LBB0_209:
	s_add_i32 s36, s19, 1
	s_cmp_ge_i32 s36, s77
	s_cbranch_scc1 .LBB0_211
	v_add_u32_e32 v50, 0x100, v135
	v_ashrrev_i32_e32 v51, 31, v50
	v_lshlrev_b64 v[50:51], 11, v[50:51]
	v_lshl_or_b32 v50, v159, 1, v50
	v_lshl_add_u64 v[52:53], s[42:43], 0, v[50:51]
	v_lshl_add_u64 v[50:51], s[40:41], 0, v[50:51]
	global_load_dwordx4 v[120:123], v[52:53], off
	global_load_dwordx4 v[124:127], v[50:51], off
	v_add_u32_e32 v50, 0x100, v134
	v_ashrrev_i32_e32 v51, 31, v50
	v_lshl_add_u64 v[50:51], v[50:51], 2, s[38:39]
	global_load_dword v165, v[50:51], off
